# convert loop waits with vmcnt(24): two to three tiles of loads stay in flight
# baseline (speedup 1.0000x reference)
; #define LAS __attribute__((address_space(3)))
; __device__ __forceinline__ int ltid() { int t = threadIdx.x; asm volatile("" : "+v"(t)); return t; }
; __device__ __forceinline__ int lbid() { int t = blockIdx.x; asm volatile("" : "+s"(t)); return t; }
; __device__ __forceinline__ CvtTile cvt_get(const Params& p, int t) {
;     const int l = t / TILES_L; int r = t % TILES_L; unsigned char* Wl = p.ws + OFF_W + (size_t)l * SZ_WL; CvtTile c; int nT; c.mode = 0; c.gk = nullptr;
;     if (r < 576) { c.W = p.w_in + (size_t)l * DM * NPROJ; c.K = DM; c.N = NPROJ; nT = 18; c.dst = (bf16_t*)(Wl + WO_IN); c.gk = p.g_mix + l * DM; }
;     else if ((r -= 576) < 48) { c.W = p.w_q_up + (size_t)l * 512 * 1536; c.K = 512; c.N = 1536; nT = 6; c.mode = 1; c.dst = (bf16_t*)(Wl + WO_Q); }
;     else if ((r -= 48) < 32) { c.W = p.w_kv_up + (size_t)l * 256 * 2048; c.K = 256; c.N = 2048; nT = 8; c.mode = 2; c.dst = (bf16_t*)(Wl + WO_KV); }
;     else if ((r -= 32) < 256) { c.W = p.w_out + (size_t)l * DM * DM; c.K = DM; c.N = DM; nT = 8; c.dst = (bf16_t*)(Wl + WO_OUT); }
;     else if ((r -= 256) < 1024) { c.W = p.w_ff1 + (size_t)l * DM * DFF; c.K = DM; c.N = DFF; nT = 32; c.dst = (bf16_t*)(Wl + WO_1); c.gk = p.g_ffn + l * DM; }
;     else { r -= 1024; c.W = p.w_ff2 + (size_t)l * DFF * DM; c.K = DFF; c.N = DM; nT = 8; c.dst = (bf16_t*)(Wl + WO_2); }
;     c.kt = r / nT; c.nt = r % nT; return c;
; }
; __device__ __forceinline__ void cvt_load(const CvtTile& c, f32x4 (&v)[8], int tid) {
; #pragma unroll
;     for (int i = 0; i < 8; ++i) { const int k = (tid >> 6) + 8 * i, gn = c.nt * 256 + (tid & 63) * 4;
;         v[i] = (f32x4){0.f, 0.f, 0.f, 0.f};
;         if (gn < c.N) { v[i] = __builtin_nontemporal_load((const f32x4*)(c.W + (size_t)(c.kt * 64 + k) * c.N + gn)); if (c.gk) v[i] = v[i] * c.gk[c.kt * 64 + k]; } }
; }
; __device__ __forceinline__ void convert_phase(const Params& p, LAS unsigned char* lds) {
;     LAS float* T = (LAS float*)lds;
;     const int tid = ltid(), G = gridDim.x;
;     int t = lbid();
;     f32x4 v[8]; CvtTile c;
;     if (t < NLAYER * TILES_L) { c = cvt_get(p, t); cvt_load(c, v, tid); }
.LBB0_537:
	s_waitcnt lgkmcnt(0)
	v_readlane_b32 s24, v252, 0
	v_readlane_b32 s25, v252, 9
	v_readlane_b32 s30, v252, 5
	v_readlane_b32 s31, v252, 6
	v_lshrrev_b32_e32 v167, 6, v192
	v_and_b32_e32 v168, 63, v192
	v_readfirstlane_b32 s28, v167
	v_lshlrev_b32_e32 v160, 4, v168
	v_mul_u32_u24_e32 v161, 8224, v167
	v_add_u32_e32 v161, v161, v160
	v_and_b32_e32 v169, 7, v192
	v_lshrrev_b32_e32 v165, 3, v192
	v_lshlrev_b32_e32 v163, 4, v169
	v_lshlrev_b32_e32 v164, 5, v169
	v_mul_u32_u24_e32 v162, 8224, v169
	s_mov_b32 s26, s24
	s_mov_b32 s27, 0
	s_mov_b32 s29, 0
	s_mov_b32 s12, 1
	s_cmp_lt_u32 s26, 11840
	s_cbranch_scc0 .Lcv_exit
	s_mov_b32 s0, 0
	s_cmp_ge_u32 s26, 2960
	s_addc_u32 s0, s0, 0
	s_cmp_ge_u32 s26, 5920
	s_addc_u32 s0, s0, 0
	s_cmp_ge_u32 s26, 8880
	s_addc_u32 s0, s0, 0
	s_mul_i32 s1, s0, 2960
	s_sub_u32 s1, s26, s1
	s_mul_i32 s2, s0, 0x5c80000
	s_cmp_lt_u32 s1, 576
	s_cbranch_scc0 .Lcv_p0_w_in_skip
	s_mul_i32 s3, s1, 3641
	s_lshr_b32 s3, s3, 16
	s_mul_i32 s4, s3, 18
	s_sub_u32 s4, s1, s4
	v_readlane_b32 s6, v253, 8
	v_readlane_b32 s7, v253, 9
	s_mul_i32 s5, s0, 0x22a0000
	s_mul_i32 s8, s3, 0x115000
	s_lshl_b32 s9, s4, 10
	s_add_u32 s5, s5, s8
	s_add_u32 s5, s5, s9
	s_add_u32 s34, s6, s5
	s_addc_u32 s35, s7, 0
	s_mov_b32 s36, 0x4540
	s_lshl_b32 s9, s4, 8
	s_mov_b32 s44, s9
	s_sub_u32 s10, 4428, s9
	s_lshl_b32 s37, s10, 2
	s_sub_u32 s45, 4431, s9
	s_add_u32 s5, s2, 0x0
	s_lshl_b32 s8, s3, 7
	s_add_u32 s5, s5, s8
	s_add_u32 s40, s30, s5
	s_addc_u32 s41, s31, 0
	s_mov_b32 s42, 12
	s_mov_b32 s43, 0
	v_readlane_b32 s6, v253, 6
	v_readlane_b32 s7, v253, 7
	s_lshl_b32 s5, s0, 13
	s_lshl_b32 s8, s3, 8
	s_add_u32 s5, s5, s8
	s_add_u32 s38, s6, s5
	s_addc_u32 s39, s7, 0
	s_mov_b32 s46, 1
	s_branch .Lcv_p0_done

; __device__ __forceinline__ void convert_phase(const Params& p, LAS unsigned char* lds) {
;     ...
;     while (t < NLAYER * TILES_L) {
; #pragma unroll
;         for (int i = 0; i < 8; ++i) { const int k = (tid >> 6) + 8 * i, n4 = (tid & 63) * 4;
;             T[k * 257 + n4] = v[i][0]; T[k * 257 + n4 + 1] = v[i][1]; T[k * 257 + n4 + 2] = v[i][2]; T[k * 257 + n4 + 3] = v[i][3]; }
;         __syncthreads();
.Lcv_loop:
	s_cmp_eq_u32 s29, 0
	s_cbranch_scc0 .Lcv_w0_0
	s_cmp_eq_u32 s12, 0
	s_cbranch_scc1 .Lcv_ws_0
	s_waitcnt vmcnt(20)
	s_branch .Lcv_w1_0
.Lcv_ws_0:
	s_waitcnt vmcnt(24)
	s_branch .Lcv_w1_0

; __device__ __forceinline__ u32x4 pack8(const float* f) { u32x4 w; w.x = cvt_pk_bf16(f[0], f[1]); w.y = cvt_pk_bf16(f[2], f[3]); w.z = cvt_pk_bf16(f[4], f[5]); w.w = cvt_pk_bf16(f[6], f[7]); return w; }
; __device__ __forceinline__ void convert_phase(const Params& p, LAS unsigned char* lds) {
;     ...
;         __syncthreads();
;         const CvtTile cur = c; const int tn = t + G;
;         if (tn < NLAYER * TILES_L) { c = cvt_get(p, tn); cvt_load(c, v, tid); }
; #pragma unroll
;         for (int i = 0; i < 4; ++i) { const int ch = tid + 512 * i, n = ch >> 3, k8 = (ch & 7) * 8, gn = cur.nt * 256 + n;
;             if (gn < cur.N) { float f[8];
; #pragma unroll
;                 for (int j = 0; j < 8; ++j) f[j] = T[(k8 + j) * 257 + n];
;                 *(u32x4*)(cur.dst + (size_t)map_col(gn, cur.mode) * cur.K + cur.kt * 64 + k8) = pack8(f); } }
;         __syncthreads();
;         t = tn;
.Lcv_nog_0:
	s_add_u32 s26, s26, s25
	s_xor_b32 s27, s27, 65792
	s_mul_i32 s0, s25, 3
	s_sub_u32 s0, s26, s0
	s_cmp_lt_u32 s0, 11840
	s_cbranch_scc0 .Lcv_exit
	s_cmp_eq_u32 s29, 0
	s_cbranch_scc0 .Lcv_w0_1
	s_cmp_eq_u32 s12, 0
	s_cbranch_scc1 .Lcv_ws_1
	s_waitcnt vmcnt(24)
	s_branch .Lcv_w1_1

; __device__ __forceinline__ u32x4 pack8(const float* f) { u32x4 w; w.x = cvt_pk_bf16(f[0], f[1]); w.y = cvt_pk_bf16(f[2], f[3]); w.z = cvt_pk_bf16(f[4], f[5]); w.w = cvt_pk_bf16(f[6], f[7]); return w; }
; __device__ __forceinline__ void convert_phase(const Params& p, LAS unsigned char* lds) {
;     ...
;         __syncthreads();
;         const CvtTile cur = c; const int tn = t + G;
;         if (tn < NLAYER * TILES_L) { c = cvt_get(p, tn); cvt_load(c, v, tid); }
; #pragma unroll
;         for (int i = 0; i < 4; ++i) { const int ch = tid + 512 * i, n = ch >> 3, k8 = (ch & 7) * 8, gn = cur.nt * 256 + n;
;             if (gn < cur.N) { float f[8];
; #pragma unroll
;                 for (int j = 0; j < 8; ++j) f[j] = T[(k8 + j) * 257 + n];
;                 *(u32x4*)(cur.dst + (size_t)map_col(gn, cur.mode) * cur.K + cur.kt * 64 + k8) = pack8(f); } }
;         __syncthreads();
;         t = tn;
.Lcv_nog_1:
	s_add_u32 s26, s26, s25
	s_xor_b32 s27, s27, 65792
	s_mul_i32 s0, s25, 3
	s_sub_u32 s0, s26, s0
	s_cmp_lt_u32 s0, 11840
	s_cbranch_scc0 .Lcv_exit
	s_cmp_eq_u32 s29, 0
	s_cbranch_scc0 .Lcv_w0_2
	s_waitcnt vmcnt(24)
	s_branch .Lcv_w1_2

; __device__ __forceinline__ void convert_phase(const Params& p, LAS unsigned char* lds) {
;     ...
;         __syncthreads();
;         t = tn;
;     }
.Lcv_nog_2:
	s_add_u32 s26, s26, s25
	s_xor_b32 s27, s27, 65792
	s_mul_i32 s0, s25, 3
	s_sub_u32 s0, s26, s0
	s_cmp_lt_u32 s0, 11840
	s_cbranch_scc0 .Lcv_exit
	s_mov_b32 s12, 0
	s_branch .Lcv_loop
